# loop-edge rotation (guide 7.11): proj and gate_up K-loops' back-edge block (barrier+counter+test) moved after the loop body so the taken branch follows the barrier instead of preceding it; body placem
# speedup vs baseline: 1.0147x; 1.0147x over previous
.LBB0_163:
	s_ashr_i32 s5, s4, 31
	s_xor_b64 s[20:21], s[10:11], -1
	s_lshl_b64 s[10:11], s[4:5], 20
	s_add_u32 s5, s92, s10
	s_addc_u32 s10, s93, s11
	s_cmp_gt_i32 s22, 0
	s_cselect_b32 s11, 0x80000, 0
	s_add_u32 s30, s5, s11
	s_addc_u32 s31, s10, 0
	s_and_b64 s[10:11], s[42:43], exec
	s_cselect_b32 s5, s31, s7
	s_cselect_b32 s47, s30, s6
	s_ashr_i32 s29, s28, 31
	s_lshl_b64 s[10:11], s[28:29], 20
	s_add_u32 s54, s88, s10
	s_addc_u32 s55, s89, s11
	s_and_b64 s[10:11], s[42:43], exec
	s_cselect_b32 s29, s55, s1
	s_cselect_b32 s68, s54, s0
	s_cmp_gt_i32 s22, -1
	s_cselect_b64 s[10:11], -1, 0
	s_and_b64 s[26:27], s[10:11], exec
	s_cselect_b32 s52, 0, 0x80000
	s_add_u32 s26, s6, 0x80
	s_addc_u32 s27, s7, 0
	v_lshl_add_u64 v[2:3], s[26:27], 0, v[218:219]
	v_lshl_add_u64 v[222:223], v[2:3], 0, s[50:51]
	v_lshl_add_u64 v[2:3], s[26:27], 0, v[220:221]
	v_lshl_add_u64 v[224:225], v[2:3], 0, s[50:51]
	v_mov_b32_e32 v2, v0
	v_mov_b32_e32 v3, v0
	s_add_u32 s69, s0, 0x100
	v_mov_b32_e32 v1, v0
	v_mov_b32_e32 v68, 0
	s_waitcnt lgkmcnt(0)
	v_mov_b64_e32 v[6:7], v[2:3]
	v_mov_b64_e32 v[10:11], v[2:3]
	v_mov_b64_e32 v[22:23], v[2:3]
	v_mov_b64_e32 v[26:27], v[2:3]
	v_mov_b64_e32 v[38:39], v[2:3]
	v_mov_b64_e32 v[42:43], v[2:3]
	v_mov_b64_e32 v[54:55], v[2:3]
	v_mov_b64_e32 v[58:59], v[2:3]
	v_mov_b64_e32 v[14:15], v[2:3]
	v_mov_b64_e32 v[18:19], v[2:3]
	v_mov_b64_e32 v[30:31], v[2:3]
	v_mov_b64_e32 v[34:35], v[2:3]
	v_mov_b64_e32 v[46:47], v[2:3]
	v_mov_b64_e32 v[50:51], v[2:3]
	v_mov_b64_e32 v[62:63], v[2:3]
	v_mov_b64_e32 v[66:67], v[2:3]
	s_addc_u32 s70, s1, 0
	s_mov_b32 s19, -2
	s_mov_b64 s[0:1], 0
	v_mov_b64_e32 v[4:5], v[0:1]
	v_mov_b64_e32 v[8:9], v[0:1]
	v_mov_b64_e32 v[20:21], v[0:1]
	v_mov_b64_e32 v[24:25], v[0:1]
	v_mov_b64_e32 v[36:37], v[0:1]
	v_mov_b64_e32 v[40:41], v[0:1]
	v_mov_b64_e32 v[52:53], v[0:1]
	v_mov_b64_e32 v[56:57], v[0:1]
	v_mov_b64_e32 v[12:13], v[0:1]
	v_mov_b64_e32 v[16:17], v[0:1]
	v_mov_b64_e32 v[28:29], v[0:1]
	v_mov_b64_e32 v[32:33], v[0:1]
	v_mov_b64_e32 v[44:45], v[0:1]
	v_mov_b64_e32 v[48:49], v[0:1]
	v_mov_b64_e32 v[60:61], v[0:1]
	v_mov_b64_e32 v[64:65], v[0:1]
	v_mov_b32_e32 v69, v68
	v_mov_b32_e32 v70, v68
	v_mov_b32_e32 v71, v68
	v_mov_b32_e32 v72, v68
	v_mov_b32_e32 v73, v68
	v_mov_b32_e32 v74, v68
	v_mov_b32_e32 v75, v68
	v_mov_b32_e32 v84, v68
	v_mov_b32_e32 v85, v68
	v_mov_b32_e32 v86, v68
	v_mov_b32_e32 v87, v68
	v_mov_b32_e32 v88, v68
	v_mov_b32_e32 v89, v68
	v_mov_b32_e32 v90, v68
	v_mov_b32_e32 v91, v68
	v_mov_b32_e32 v100, v68
	v_mov_b32_e32 v101, v68
	v_mov_b32_e32 v102, v68
	v_mov_b32_e32 v103, v68
	v_mov_b32_e32 v104, v68
	v_mov_b32_e32 v105, v68
	v_mov_b32_e32 v106, v68
	v_mov_b32_e32 v107, v68
	v_mov_b32_e32 v116, v68
	v_mov_b32_e32 v117, v68
	v_mov_b32_e32 v118, v68
	v_mov_b32_e32 v119, v68
	v_mov_b32_e32 v120, v68
	v_mov_b32_e32 v121, v68
	v_mov_b32_e32 v122, v68
	v_mov_b32_e32 v123, v68
	v_mov_b32_e32 v76, v68
	v_mov_b32_e32 v77, v68
	v_mov_b32_e32 v78, v68
	v_mov_b32_e32 v79, v68
	v_mov_b32_e32 v80, v68
	v_mov_b32_e32 v81, v68
	v_mov_b32_e32 v82, v68
	v_mov_b32_e32 v83, v68
	v_mov_b32_e32 v92, v68
	v_mov_b32_e32 v93, v68
	v_mov_b32_e32 v94, v68
	v_mov_b32_e32 v95, v68
	v_mov_b32_e32 v96, v68
	v_mov_b32_e32 v97, v68
	v_mov_b32_e32 v98, v68
	v_mov_b32_e32 v99, v68
	v_mov_b32_e32 v108, v68
	v_mov_b32_e32 v109, v68
	v_mov_b32_e32 v110, v68
	v_mov_b32_e32 v111, v68
	v_mov_b32_e32 v112, v68
	v_mov_b32_e32 v113, v68
	v_mov_b32_e32 v114, v68
	v_mov_b32_e32 v115, v68
	v_mov_b32_e32 v124, v68
	v_mov_b32_e32 v125, v68
	v_mov_b32_e32 v126, v68
	v_mov_b32_e32 v127, v68
	v_mov_b32_e32 v128, v68
	v_mov_b32_e32 v129, v68
	v_mov_b32_e32 v130, v68
	v_mov_b32_e32 v131, v68
	s_mov_b32 s25, s44
	s_branch .LBB0_165
	s_nop 0
	s_nop 0
	s_nop 0
	s_nop 0
	s_nop 0
	s_nop 0
	s_nop 0

.LBB0_164:
	s_barrier
	s_add_i32 s19, s19, 2
	s_add_u32 s0, s0, 0x100
	s_addc_u32 s1, s1, 0
	s_cmp_gt_u32 s19, 29
	s_cbranch_scc0 .LBB0_165
.LBB0_173:
	s_nop 0
	s_nop 0
	s_and_b64 vcc, exec, s[14:15]
	s_cbranch_vccz .LBB0_175
	s_barrier

.LBB0_679:
	s_xor_b64 s[14:15], s[0:1], -1
	s_and_b64 s[0:1], s[44:45], exec
	v_readlane_b32 s0, v254, 31
	s_cselect_b32 s74, s0, -1
	s_ashr_i32 s55, s54, 31
	s_lshl_b64 s[0:1], s[54:55], 20
	s_add_u32 s0, s19, s0
	s_addc_u32 s1, s23, s1
	s_cmp_gt_i32 s74, 0
	s_cselect_b32 s20, 0x80000, 0
	s_add_u32 s56, s0, s20
	s_addc_u32 s57, s1, 0
	s_and_b64 s[0:1], s[38:39], exec
	s_cselect_b32 s33, s57, s11
	s_cselect_b32 s34, s56, s10
	s_ashr_i32 s47, s46, 31
	s_lshl_b64 s[0:1], s[46:47], 20
	s_add_u32 s58, s29, s0
	s_addc_u32 s59, s30, s1
	s_and_b64 s[0:1], s[38:39], exec
	s_cselect_b32 s35, s59, s17
	s_cselect_b32 s47, s58, s16
	s_and_b64 s[0:1], s[44:45], exec
	s_cselect_b32 s52, 0, 0x80000
	s_add_u32 s0, s10, 0x80
	s_addc_u32 s1, s11, 0
	v_lshl_add_u64 v[2:3], s[0:1], 0, v[216:217]
	v_lshl_add_u64 v[220:221], v[2:3], 0, s[12:13]
	v_lshl_add_u64 v[2:3], s[0:1], 0, v[218:219]
	v_lshl_add_u64 v[222:223], v[2:3], 0, s[12:13]
	v_mov_b32_e32 v2, v0
	v_mov_b32_e32 v3, v0
	s_add_u32 s55, s16, 0x100
	v_mov_b32_e32 v1, v0
	v_mov_b32_e32 v68, 0
	v_mov_b64_e32 v[6:7], v[2:3]
	v_mov_b64_e32 v[10:11], v[2:3]
	v_mov_b64_e32 v[22:23], v[2:3]
	v_mov_b64_e32 v[26:27], v[2:3]
	v_mov_b64_e32 v[38:39], v[2:3]
	v_mov_b64_e32 v[42:43], v[2:3]
	v_mov_b64_e32 v[54:55], v[2:3]
	v_mov_b64_e32 v[58:59], v[2:3]
	v_mov_b64_e32 v[14:15], v[2:3]
	v_mov_b64_e32 v[18:19], v[2:3]
	v_mov_b64_e32 v[30:31], v[2:3]
	v_mov_b64_e32 v[34:35], v[2:3]
	v_mov_b64_e32 v[46:47], v[2:3]
	v_mov_b64_e32 v[50:51], v[2:3]
	v_mov_b64_e32 v[62:63], v[2:3]
	v_mov_b64_e32 v[66:67], v[2:3]
	s_addc_u32 s68, s17, 0
	s_mov_b32 s69, -2
	s_mov_b64 s[0:1], 0
	v_mov_b64_e32 v[4:5], v[0:1]
	v_mov_b64_e32 v[8:9], v[0:1]
	v_mov_b64_e32 v[20:21], v[0:1]
	v_mov_b64_e32 v[24:25], v[0:1]
	v_mov_b64_e32 v[36:37], v[0:1]
	v_mov_b64_e32 v[40:41], v[0:1]
	v_mov_b64_e32 v[52:53], v[0:1]
	v_mov_b64_e32 v[56:57], v[0:1]
	v_mov_b64_e32 v[12:13], v[0:1]
	v_mov_b64_e32 v[16:17], v[0:1]
	v_mov_b64_e32 v[28:29], v[0:1]
	v_mov_b64_e32 v[32:33], v[0:1]
	v_mov_b64_e32 v[44:45], v[0:1]
	v_mov_b64_e32 v[48:49], v[0:1]
	v_mov_b64_e32 v[60:61], v[0:1]
	v_mov_b64_e32 v[64:65], v[0:1]
	v_mov_b32_e32 v69, v68
	v_mov_b32_e32 v70, v68
	v_mov_b32_e32 v71, v68
	v_mov_b32_e32 v72, v68
	v_mov_b32_e32 v73, v68
	v_mov_b32_e32 v74, v68
	v_mov_b32_e32 v75, v68
	v_mov_b32_e32 v84, v68
	v_mov_b32_e32 v85, v68
	v_mov_b32_e32 v86, v68
	v_mov_b32_e32 v87, v68
	v_mov_b32_e32 v88, v68
	v_mov_b32_e32 v89, v68
	v_mov_b32_e32 v90, v68
	v_mov_b32_e32 v91, v68
	v_mov_b32_e32 v100, v68
	v_mov_b32_e32 v101, v68
	v_mov_b32_e32 v102, v68
	v_mov_b32_e32 v103, v68
	v_mov_b32_e32 v104, v68
	v_mov_b32_e32 v105, v68
	v_mov_b32_e32 v106, v68
	v_mov_b32_e32 v107, v68
	v_mov_b32_e32 v116, v68
	v_mov_b32_e32 v117, v68
	v_mov_b32_e32 v118, v68
	v_mov_b32_e32 v119, v68
	v_mov_b32_e32 v120, v68
	v_mov_b32_e32 v121, v68
	v_mov_b32_e32 v122, v68
	v_mov_b32_e32 v123, v68
	v_mov_b32_e32 v76, v68
	v_mov_b32_e32 v77, v68
	v_mov_b32_e32 v78, v68
	v_mov_b32_e32 v79, v68
	v_mov_b32_e32 v80, v68
	v_mov_b32_e32 v81, v68
	v_mov_b32_e32 v82, v68
	v_mov_b32_e32 v83, v68
	v_mov_b32_e32 v92, v68
	v_mov_b32_e32 v93, v68
	v_mov_b32_e32 v94, v68
	v_mov_b32_e32 v95, v68
	v_mov_b32_e32 v96, v68
	v_mov_b32_e32 v97, v68
	v_mov_b32_e32 v98, v68
	v_mov_b32_e32 v99, v68
	v_mov_b32_e32 v108, v68
	v_mov_b32_e32 v109, v68
	v_mov_b32_e32 v110, v68
	v_mov_b32_e32 v111, v68
	v_mov_b32_e32 v112, v68
	v_mov_b32_e32 v113, v68
	v_mov_b32_e32 v114, v68
	v_mov_b32_e32 v115, v68
	v_mov_b32_e32 v124, v68
	v_mov_b32_e32 v125, v68
	v_mov_b32_e32 v126, v68
	v_mov_b32_e32 v127, v68
	v_mov_b32_e32 v128, v68
	v_mov_b32_e32 v129, v68
	v_mov_b32_e32 v130, v68
	v_mov_b32_e32 v131, v68
	s_branch .LBB0_681
	s_nop 0
	s_nop 0
	s_nop 0
	s_nop 0
	s_nop 0
	s_nop 0
	s_nop 0

.LBB0_680:
	s_barrier
	s_add_i32 s69, s69, 2
	s_add_u32 s0, s0, 0x100
	s_addc_u32 s1, s1, 0
	s_cmp_gt_u32 s69, 29
	s_cbranch_scc0 .LBB0_681
.LBB0_689:
	s_nop 0
	s_nop 0
	s_and_b64 vcc, exec, s[42:43]
	s_cbranch_vccz .LBB0_691
	s_barrier
